# scan loop: additionally merged 27 paired lgkmcnt waits per 32 steps into single waits (counts re-derived and checked); scan loop placed +16 bytes
# speedup vs baseline: 1.0042x; 1.0005x over previous
; DEVI void scan_item(const Params& p, int l, int item, unsigned char* smem) {
;     ...
;   const int tl = tid >> 4, cg4 = (tid & 15) * 4;
;   const f32x4 kkc = *(const f32x4*)(p.k_k + l * 512 + h * 64 + cg4);
;   const f32x4 kac = *(const f32x4*)(p.k_a + l * 512 + h * 64 + cg4);
;   ScRaw RA, RB;
;   RA.gv[0] = 0; RA.gv[1] = 0; RB.gv[0] = 0; RB.gv[1] = 0;
;     ...
;   SC_LOAD(0, RA);
;   SC_LOAD(1, RB);
;   SC_STAGE(0, RA);
;   __syncthreads();
;   f32x2 S01 = {0.f, 0.f}, S23 = {0.f, 0.f};
;   const int vidx = 320 + wave * 4 + rl;
;   const bool bit3 = (kl & 8) != 0, bit2 = (kl & 4) != 0, bit1 = (kl & 2) != 0, bit0 = (kl & 1) != 0;
;   __builtin_amdgcn_s_setprio(3);
.LBB0_190:
	s_or_b64 exec, exec, s[42:43]
	v_ashrrev_i32_e32 v9, 31, v8
	v_lshlrev_b64 v[10:11], 10, v[8:9]
	v_lshl_add_u64 v[18:19], s[30:31], 0, v[10:11]
	v_lshl_add_u64 v[18:19], v[18:19], 0, s[96:97]
	v_lshl_add_u64 v[10:11], s[22:23], 0, v[10:11]
	v_lshl_or_b32 v8, v8, 3, s24
	v_readlane_b32 s42, v253, 24
	v_lshl_add_u64 v[18:19], v[18:19], 0, v[162:163]
	v_lshl_add_u64 v[10:11], v[10:11], 0, s[96:97]
	v_ashrrev_i32_e32 v9, 31, v8
	v_readlane_b32 s43, v253, 25
	v_lshl_add_u64 v[10:11], v[10:11], 0, v[162:163]
	s_waitcnt vmcnt(4)
	v_cvt_f32_f16_e32 v24, v75
	v_lshl_add_u64 v[8:9], v[8:9], 2, s[42:43]
	global_load_dwordx2 v[86:87], v[18:19], off
	global_load_dwordx2 v[88:89], v[10:11], off
	global_load_dword v90, v[8:9], off
	v_cvt_f32_f16_e32 v18, v74
	v_cvt_f32_f16_sdwa v19, v74 dst_sel:DWORD dst_unused:UNUSED_PAD src0_sel:WORD_1
	v_cvt_f32_f16_sdwa v25, v75 dst_sel:DWORD dst_unused:UNUSED_PAD src0_sel:WORD_1
	v_lshlrev_b32_e32 v30, 16, v72
	v_and_b32_e32 v31, 0xffff0000, v72
	s_waitcnt vmcnt(6)
	v_cvt_f32_f16_sdwa v33, v76 dst_sel:DWORD dst_unused:UNUSED_PAD src0_sel:WORD_1
	v_cvt_f32_f16_e32 v32, v76
	v_pk_mul_f32 v[20:21], v[0:1], v[30:31]
	v_cvt_f32_f16_sdwa v37, v77 dst_sel:DWORD dst_unused:UNUSED_PAD src0_sel:WORD_1
	v_cvt_f32_f16_e32 v36, v77
	v_mul_f32_e32 v18, 0x3fb8aa3b, v18
	v_mul_f32_e32 v19, 0x3fb8aa3b, v19
	s_waitcnt vmcnt(5)
	v_pk_mul_f32 v[22:23], v[20:21], v[78:79] op_sel_hi:[1,0]
	v_mul_f32_e32 v20, 0x3fb8aa3b, v24
	v_mul_f32_e32 v21, 0x3fb8aa3b, v25
	v_lshlrev_b32_e32 v34, 16, v73
	v_and_b32_e32 v35, 0xffff0000, v73
	v_exp_f32_e32 v18, v18
	v_exp_f32_e32 v19, v19
	v_exp_f32_e32 v20, v20
	v_exp_f32_e32 v21, v21
	v_pk_mul_f32 v[24:25], v[2:3], v[34:35]
	s_movk_i32 s2, 0x540
	v_pk_mul_f32 v[24:25], v[24:25], v[78:79] op_sel_hi:[1,0]
	v_mul_lo_u32 v17, v13, s2
	v_pk_mul_f32 v[28:29], v[36:37], v[24:25] neg_lo:[0,1] neg_hi:[0,1]
	v_pk_mul_f32 v[26:27], v[32:33], v[22:23] neg_lo:[0,1] neg_hi:[0,1]
	v_pk_add_f32 v[32:33], v[32:33], -1.0 op_sel_hi:[1,0]
	v_pk_add_f32 v[36:37], v[36:37], -1.0 op_sel_hi:[1,0]
	v_pk_fma_f32 v[38:39], v[4:5], v[32:33], 1.0 op_sel_hi:[1,1,0]
	v_pk_fma_f32 v[36:37], v[6:7], v[36:37], 1.0 op_sel_hi:[1,1,0]
	v_lshl_add_u32 v79, v15, 2, v17
	v_lshlrev_b32_e32 v8, 16, v70
	v_and_b32_e32 v9, 0xffff0000, v70
	v_lshlrev_b32_e32 v10, 16, v71
	v_and_b32_e32 v11, 0xffff0000, v71
	v_pk_mul_f32 v[32:33], v[36:37], v[34:35]
	v_pk_mul_f32 v[30:31], v[38:39], v[30:31]
	ds_write_b128 v79, v[18:21]
	ds_write_b128 v79, v[22:25] offset:256
	ds_write_b128 v79, v[26:29] offset:512
	ds_write_b128 v79, v[30:33] offset:768
	ds_write_b128 v79, v[8:11] offset:1024
	s_and_saveexec_b64 s[42:43], s[40:41]
	v_lshlrev_b32_e32 v8, 16, v68
	v_and_b32_e32 v9, 0xffff0000, v68
	v_lshlrev_b32_e32 v10, 16, v69
	v_and_b32_e32 v11, 0xffff0000, v69
	ds_write_b128 v79, v[8:11] offset:1280
	s_or_b64 exec, exec, s[42:43]
	v_and_b32_e32 v11, 8, v14
	v_cmp_eq_u32_e64 s[42:43], 0, v11
	v_and_b32_e32 v11, 4, v14
	v_cmp_eq_u32_e64 s[44:45], 0, v11
	v_and_b32_e32 v11, 2, v14
	v_cmp_eq_u32_e64 s[46:47], 0, v11
	v_and_b32_e32 v11, 1, v14
	v_lshrrev_b32_e32 v8, 4, v14
	v_bfe_u32 v9, v14, 4, 2
	s_add_u32 s37, s28, s25
	v_and_b32_e32 v10, -4, v13
	s_mov_b32 s25, 0
	v_cmp_eq_u32_e64 s[48:49], 0, v11
	s_addc_u32 s50, s29, 0
	s_waitcnt lgkmcnt(0)
	s_barrier
	s_setprio 3
	s_add_u32 s30, s30, s96
	s_addc_u32 s31, s31, 0
	v_lshlrev_b32_e32 v96, 2, v15
	v_bfi_b32 v8, -4, v13, v8
	s_add_u32 s22, s22, s96
	v_lshlrev_b32_e32 v91, 2, v8
	v_mad_u32_u24 v11, v12, 48, v96
	v_lshlrev_b32_e32 v8, 2, v10
	v_lshlrev_b32_e32 v9, 2, v9
	s_addc_u32 s23, s23, 0
	v_add3_u32 v97, v11, v8, v9
	v_lshl_add_u64 v[94:95], s[22:23], 0, v[162:163]
	v_mad_u64_u32 v[98:99], s[22:23], v16, s2, v[96:97]
	s_lshl_b32 s26, s27, 4
	s_add_u32 s22, s37, s96
	s_addc_u32 s23, s50, 0
	s_lshl_b32 s27, s27, 5
	s_add_u32 s22, s22, s27
	s_addc_u32 s23, s23, 0
	v_lshlrev_b32_e32 v8, 1, v12
	v_mov_b32_e32 v9, v163
	s_lshl_b32 s27, s36, 13
	s_lshl_b32 s36, s36, 8
	v_lshl_add_u64 v[100:101], s[22:23], 0, v[8:9]
	s_bitset1_b32 s36, 15
	v_readlane_b32 s22, v253, 7
	s_movk_i32 s2, 0xffd0
	v_readlane_b32 s23, v253, 8
	s_add_u32 s22, s22, s96
	v_mov_b32_e32 v8, 0
	v_lshl_add_u64 v[92:93], s[30:31], 0, v[162:163]
	v_lshlrev_b32_e32 v99, 2, v14
	v_mad_i32_i24 v103, v12, s2, v11
	s_addc_u32 s23, s23, 0
	v_sub_u32_e32 v105, 0, v13
	v_add_u32_e32 v112, 48, v13
	v_mov_b32_e32 v9, v8
	v_mov_b32_e32 v10, v8
	v_mov_b32_e32 v11, v8
	s_branch .LBB0_195
	s_nop 0
	s_nop 0
	s_nop 0
	s_nop 0
.LBB0_193:
	s_or_b64 exec, exec, s[50:51]

; DEVI float allreduce16(float v) {
;   v = dpp_add<0xB1>(v);
;   v = dpp_add<0x4E>(v);
;   v = dpp_add<0x141>(v);
;   v = dpp_add<0x140>(v);
;   return v;
; }
.LBB0_199:
	ds_read_b128 v[12:15], v96
	ds_read_b128 v[16:19], v96 offset:256
	ds_read_b128 v[20:23], v96 offset:512
	ds_read_b128 v[24:27], v96 offset:768
	ds_read_b128 v[28:31], v96 offset:1024
	ds_read_b32 v102, v91 offset:1280
	ds_read_b128 v[32:35], v96 offset:1344
	ds_read_b128 v[36:39], v96 offset:1600
	ds_read_b128 v[40:43], v96 offset:1856
	ds_read_b128 v[44:47], v96 offset:2112
	ds_read_b128 v[48:51], v96 offset:2368
	ds_read_b32 v104, v91 offset:2624
	s_waitcnt lgkmcnt(6)
	v_pk_mul_f32 v[16:17], v[8:9], v[16:17]
	s_nop 0
	v_pk_fma_f32 v[16:17], v[10:11], v[18:19], v[16:17]
	v_pk_mul_f32 v[18:19], v[26:27], v[102:103] op_sel_hi:[1,0]
	v_add_f32_e32 v111, v16, v17
	v_pk_mul_f32 v[16:17], v[24:25], v[102:103] op_sel_hi:[1,0]
	v_pk_fma_f32 v[10:11], v[10:11], v[14:15], v[18:19]
	v_pk_fma_f32 v[8:9], v[8:9], v[12:13], v[16:17]
	v_add_f32_dpp v12, v111, v111 quad_perm:[1,0,3,2] row_mask:0xf bank_mask:0xf bound_ctrl:1
	ds_read_b128 v[52:55], v96 offset:2688
	ds_read_b128 v[56:59], v96 offset:2944
	v_add_f32_dpp v12, v12, v12 quad_perm:[2,3,0,1] row_mask:0xf bank_mask:0xf bound_ctrl:1
	ds_read_b128 v[60:63], v96 offset:3200
	ds_read_b128 v[64:67], v96 offset:3456
	v_add_f32_dpp v12, v12, v12 row_half_mirror row_mask:0xf bank_mask:0xf bound_ctrl:1
	ds_read_b128 v[106:109], v96 offset:3712
	ds_read_b32 v110, v91 offset:3968
	v_add_f32_dpp v12, v12, v12 row_mirror row_mask:0xf bank_mask:0xf bound_ctrl:1
	v_pk_fma_f32 v[8:9], v[20:21], v[12:13], v[8:9] op_sel_hi:[1,0,1]
	v_pk_fma_f32 v[10:11], v[22:23], v[12:13], v[10:11] op_sel_hi:[1,0,1]
	v_pk_mul_f32 v[12:13], v[28:29], v[8:9]
	s_nop 0
	v_pk_fma_f32 v[12:13], v[30:31], v[10:11], v[12:13]
	v_add_f32_e32 v113, v12, v13
	s_waitcnt lgkmcnt(6)
	v_pk_mul_f32 v[12:13], v[36:37], v[8:9]
	v_pk_mul_f32 v[8:9], v[32:33], v[8:9]
	v_pk_fma_f32 v[12:13], v[38:39], v[10:11], v[12:13]
	v_pk_fma_f32 v[8:9], v[44:45], v[104:105], v[8:9] op_sel_hi:[1,0,1]
	v_add_f32_e32 v12, v12, v13
	v_pk_mul_f32 v[10:11], v[34:35], v[10:11]
	ds_read_b128 v[28:31], v96 offset:4032
	v_add_f32_dpp v12, v12, v12 quad_perm:[1,0,3,2] row_mask:0xf bank_mask:0xf bound_ctrl:1
	v_pk_fma_f32 v[10:11], v[46:47], v[104:105], v[10:11] op_sel_hi:[1,0,1]
	ds_read_b128 v[116:119], v96 offset:4288
	v_add_f32_dpp v12, v12, v12 quad_perm:[2,3,0,1] row_mask:0xf bank_mask:0xf bound_ctrl:1
	ds_read_b128 v[120:123], v96 offset:4544
	ds_read_b128 v[124:127], v96 offset:4800
	v_add_f32_dpp v12, v12, v12 row_half_mirror row_mask:0xf bank_mask:0xf bound_ctrl:1
	ds_read_b128 v[128:131], v96 offset:5056
	ds_read_b32 v148, v91 offset:5312
	v_add_f32_dpp v12, v12, v12 row_mirror row_mask:0xf bank_mask:0xf bound_ctrl:1
	v_pk_fma_f32 v[8:9], v[40:41], v[12:13], v[8:9] op_sel_hi:[1,0,1]
	v_pk_fma_f32 v[10:11], v[42:43], v[12:13], v[10:11] op_sel_hi:[1,0,1]
	v_pk_mul_f32 v[12:13], v[48:49], v[8:9]
	s_nop 0
	v_pk_fma_f32 v[12:13], v[50:51], v[10:11], v[12:13]
	v_add_f32_e32 v114, v12, v13
	s_waitcnt lgkmcnt(6)
	v_pk_mul_f32 v[12:13], v[56:57], v[8:9]
	v_pk_mul_f32 v[8:9], v[52:53], v[8:9]
	v_pk_fma_f32 v[12:13], v[58:59], v[10:11], v[12:13]
	v_pk_fma_f32 v[8:9], v[64:65], v[110:111], v[8:9] op_sel_hi:[1,0,1]
	v_add_f32_e32 v12, v12, v13
	v_pk_mul_f32 v[10:11], v[54:55], v[10:11]
	ds_read_b128 v[48:51], v96 offset:5376
	v_add_f32_dpp v12, v12, v12 quad_perm:[1,0,3,2] row_mask:0xf bank_mask:0xf bound_ctrl:1
	v_pk_fma_f32 v[10:11], v[66:67], v[110:111], v[10:11] op_sel_hi:[1,0,1]
	ds_read_b128 v[132:135], v96 offset:5632
	v_add_f32_dpp v12, v12, v12 quad_perm:[2,3,0,1] row_mask:0xf bank_mask:0xf bound_ctrl:1
	ds_read_b128 v[136:139], v96 offset:5888
	ds_read_b128 v[140:143], v96 offset:6144
	v_add_f32_dpp v12, v12, v12 row_half_mirror row_mask:0xf bank_mask:0xf bound_ctrl:1
	ds_read_b128 v[144:147], v96 offset:6400
	ds_read_b32 v150, v91 offset:6656
	v_add_f32_dpp v12, v12, v12 row_mirror row_mask:0xf bank_mask:0xf bound_ctrl:1
	v_pk_fma_f32 v[32:33], v[60:61], v[12:13], v[8:9] op_sel_hi:[1,0,1]
	v_pk_fma_f32 v[34:35], v[62:63], v[12:13], v[10:11] op_sel_hi:[1,0,1]
	s_waitcnt lgkmcnt(6)
	v_pk_mul_f32 v[36:37], v[116:117], v[32:33]
	v_pk_mul_f32 v[8:9], v[106:107], v[32:33]
	v_pk_fma_f32 v[36:37], v[118:119], v[34:35], v[36:37]
	v_pk_mul_f32 v[28:29], v[28:29], v[32:33]
	v_add_f32_e32 v36, v36, v37
	v_pk_fma_f32 v[28:29], v[124:125], v[148:149], v[28:29] op_sel_hi:[1,0,1]
	v_pk_mul_f32 v[30:31], v[30:31], v[34:35]
	v_add_f32_dpp v32, v36, v36 quad_perm:[1,0,3,2] row_mask:0xf bank_mask:0xf bound_ctrl:1
	v_pk_fma_f32 v[30:31], v[126:127], v[148:149], v[30:31] op_sel_hi:[1,0,1]
	v_pk_fma_f32 v[8:9], v[108:109], v[34:35], v[8:9]
	v_add_f32_dpp v32, v32, v32 quad_perm:[2,3,0,1] row_mask:0xf bank_mask:0xf bound_ctrl:1
	v_add_f32_e32 v115, v8, v9
	ds_read_b128 v[16:19], v96 offset:6720
	ds_read_b128 v[24:27], v96 offset:6976
	ds_read_b128 v[12:15], v96 offset:7232
	ds_read_b128 v[20:23], v96 offset:7488
	v_add_f32_dpp v32, v32, v32 row_half_mirror row_mask:0xf bank_mask:0xf bound_ctrl:1
	ds_read_b128 v[8:11], v96 offset:7744
	ds_read_b32 v102, v91 offset:8000
	v_add_f32_dpp v32, v32, v32 row_mirror row_mask:0xf bank_mask:0xf bound_ctrl:1
	v_pk_fma_f32 v[52:53], v[120:121], v[32:33], v[28:29] op_sel_hi:[1,0,1]
	v_pk_fma_f32 v[54:55], v[122:123], v[32:33], v[30:31] op_sel_hi:[1,0,1]
	s_waitcnt lgkmcnt(6)
	v_pk_mul_f32 v[56:57], v[132:133], v[52:53]
	v_pk_mul_f32 v[28:29], v[128:129], v[52:53]
	v_pk_fma_f32 v[56:57], v[134:135], v[54:55], v[56:57]
	v_pk_mul_f32 v[48:49], v[48:49], v[52:53]
	v_add_f32_e32 v56, v56, v57
	v_pk_fma_f32 v[48:49], v[140:141], v[150:151], v[48:49] op_sel_hi:[1,0,1]
	v_pk_mul_f32 v[50:51], v[50:51], v[54:55]
	v_add_f32_dpp v52, v56, v56 quad_perm:[1,0,3,2] row_mask:0xf bank_mask:0xf bound_ctrl:1
	v_pk_fma_f32 v[50:51], v[142:143], v[150:151], v[50:51] op_sel_hi:[1,0,1]
	v_pk_fma_f32 v[28:29], v[130:131], v[54:55], v[28:29]
	v_add_f32_dpp v52, v52, v52 quad_perm:[2,3,0,1] row_mask:0xf bank_mask:0xf bound_ctrl:1
	v_add_f32_e32 v116, v28, v29
	ds_read_b128 v[36:39], v96 offset:8064
	ds_read_b128 v[44:47], v96 offset:8320
	ds_read_b128 v[32:35], v96 offset:8576
	ds_read_b128 v[40:43], v96 offset:8832
	v_add_f32_dpp v52, v52, v52 row_half_mirror row_mask:0xf bank_mask:0xf bound_ctrl:1
	ds_read_b128 v[28:31], v96 offset:9088
	ds_read_b32 v104, v91 offset:9344
	v_add_f32_dpp v52, v52, v52 row_mirror row_mask:0xf bank_mask:0xf bound_ctrl:1
	v_pk_fma_f32 v[110:111], v[136:137], v[52:53], v[48:49] op_sel_hi:[1,0,1]
	v_pk_fma_f32 v[108:109], v[138:139], v[52:53], v[50:51] op_sel_hi:[1,0,1]
	s_waitcnt lgkmcnt(6)
	v_pk_mul_f32 v[24:25], v[24:25], v[110:111]
	v_pk_mul_f32 v[16:17], v[16:17], v[110:111]
	v_pk_fma_f32 v[24:25], v[26:27], v[108:109], v[24:25]
	v_pk_fma_f32 v[16:17], v[20:21], v[102:103], v[16:17] op_sel_hi:[1,0,1]
	v_add_f32_e32 v24, v24, v25
	v_pk_mul_f32 v[48:49], v[144:145], v[110:111]
	v_pk_mul_f32 v[18:19], v[18:19], v[108:109]
	v_add_f32_dpp v20, v24, v24 quad_perm:[1,0,3,2] row_mask:0xf bank_mask:0xf bound_ctrl:1
	v_pk_fma_f32 v[48:49], v[146:147], v[108:109], v[48:49]
	v_pk_fma_f32 v[18:19], v[22:23], v[102:103], v[18:19] op_sel_hi:[1,0,1]
	v_add_f32_dpp v20, v20, v20 quad_perm:[2,3,0,1] row_mask:0xf bank_mask:0xf bound_ctrl:1
	v_add_f32_e32 v117, v48, v49
	ds_read_b128 v[56:59], v96 offset:9408
	ds_read_b128 v[64:67], v96 offset:9664
	ds_read_b128 v[52:55], v96 offset:9920
	ds_read_b128 v[60:63], v96 offset:10176
	v_add_f32_dpp v20, v20, v20 row_half_mirror row_mask:0xf bank_mask:0xf bound_ctrl:1
	ds_read_b128 v[48:51], v96 offset:10432
	ds_read_b32 v106, v91 offset:10688
	v_add_f32_dpp v20, v20, v20 row_mirror row_mask:0xf bank_mask:0xf bound_ctrl:1
	v_pk_fma_f32 v[108:109], v[12:13], v[20:21], v[16:17] op_sel_hi:[1,0,1]
	v_pk_fma_f32 v[118:119], v[14:15], v[20:21], v[18:19] op_sel_hi:[1,0,1]
	s_waitcnt lgkmcnt(6)
	v_pk_mul_f32 v[44:45], v[44:45], v[108:109]
	v_pk_mul_f32 v[36:37], v[36:37], v[108:109]
	v_pk_fma_f32 v[44:45], v[46:47], v[118:119], v[44:45]
	v_pk_fma_f32 v[36:37], v[40:41], v[104:105], v[36:37] op_sel_hi:[1,0,1]
	v_add_f32_e32 v44, v44, v45
	v_pk_mul_f32 v[38:39], v[38:39], v[118:119]
	v_pk_mul_f32 v[8:9], v[8:9], v[108:109]
	v_add_f32_dpp v40, v44, v44 quad_perm:[1,0,3,2] row_mask:0xf bank_mask:0xf bound_ctrl:1
	v_pk_fma_f32 v[38:39], v[42:43], v[104:105], v[38:39] op_sel_hi:[1,0,1]
	v_pk_fma_f32 v[8:9], v[10:11], v[118:119], v[8:9]
	v_add_f32_dpp v40, v40, v40 quad_perm:[2,3,0,1] row_mask:0xf bank_mask:0xf bound_ctrl:1
	v_add_f32_e32 v111, v8, v9
	ds_read_b128 v[8:11], v96 offset:10752
	ds_read_b128 v[12:15], v96 offset:11008
	ds_read_b128 v[16:19], v96 offset:11264
	ds_read_b128 v[20:23], v96 offset:11520
	v_add_f32_dpp v40, v40, v40 row_half_mirror row_mask:0xf bank_mask:0xf bound_ctrl:1
	ds_read_b128 v[24:27], v96 offset:11776
	ds_read_b32 v102, v91 offset:12032
	v_add_f32_dpp v40, v40, v40 row_mirror row_mask:0xf bank_mask:0xf bound_ctrl:1
	v_pk_fma_f32 v[108:109], v[32:33], v[40:41], v[36:37] op_sel_hi:[1,0,1]
	v_pk_fma_f32 v[120:121], v[34:35], v[40:41], v[38:39] op_sel_hi:[1,0,1]
	s_waitcnt lgkmcnt(6)
	v_pk_mul_f32 v[64:65], v[64:65], v[108:109]
	v_pk_mul_f32 v[56:57], v[56:57], v[108:109]
	v_pk_fma_f32 v[64:65], v[66:67], v[120:121], v[64:65]
	v_pk_fma_f32 v[56:57], v[60:61], v[106:107], v[56:57] op_sel_hi:[1,0,1]
	v_add_f32_e32 v64, v64, v65
	v_pk_mul_f32 v[58:59], v[58:59], v[120:121]
	v_pk_mul_f32 v[28:29], v[28:29], v[108:109]
	v_add_f32_dpp v60, v64, v64 quad_perm:[1,0,3,2] row_mask:0xf bank_mask:0xf bound_ctrl:1
	v_pk_fma_f32 v[58:59], v[62:63], v[106:107], v[58:59] op_sel_hi:[1,0,1]
	v_pk_fma_f32 v[28:29], v[30:31], v[120:121], v[28:29]
	v_add_f32_dpp v60, v60, v60 quad_perm:[2,3,0,1] row_mask:0xf bank_mask:0xf bound_ctrl:1
	v_add_f32_e32 v118, v28, v29
	ds_read_b128 v[28:31], v96 offset:12096
	ds_read_b128 v[32:35], v96 offset:12352
	ds_read_b128 v[36:39], v96 offset:12608
	ds_read_b128 v[40:43], v96 offset:12864
	v_add_f32_dpp v60, v60, v60 row_half_mirror row_mask:0xf bank_mask:0xf bound_ctrl:1
	ds_read_b128 v[44:47], v96 offset:13120
	ds_read_b32 v104, v91 offset:13376
	v_add_f32_dpp v60, v60, v60 row_mirror row_mask:0xf bank_mask:0xf bound_ctrl:1
	v_pk_fma_f32 v[106:107], v[52:53], v[60:61], v[56:57] op_sel_hi:[1,0,1]
	v_pk_fma_f32 v[108:109], v[54:55], v[60:61], v[58:59] op_sel_hi:[1,0,1]
	s_waitcnt lgkmcnt(6)
	v_pk_mul_f32 v[12:13], v[12:13], v[106:107]
	v_pk_mul_f32 v[8:9], v[8:9], v[106:107]
	v_pk_fma_f32 v[12:13], v[14:15], v[108:109], v[12:13]
	v_pk_fma_f32 v[8:9], v[20:21], v[102:103], v[8:9] op_sel_hi:[1,0,1]
	v_add_f32_e32 v12, v12, v13
	v_pk_mul_f32 v[10:11], v[10:11], v[108:109]
	v_pk_mul_f32 v[48:49], v[48:49], v[106:107]
	v_add_f32_dpp v12, v12, v12 quad_perm:[1,0,3,2] row_mask:0xf bank_mask:0xf bound_ctrl:1
	v_pk_fma_f32 v[10:11], v[22:23], v[102:103], v[10:11] op_sel_hi:[1,0,1]
	v_pk_fma_f32 v[48:49], v[50:51], v[108:109], v[48:49]
	v_add_f32_dpp v12, v12, v12 quad_perm:[2,3,0,1] row_mask:0xf bank_mask:0xf bound_ctrl:1
	v_add_f32_e32 v119, v48, v49
	ds_read_b128 v[48:51], v96 offset:13440
	ds_read_b128 v[52:55], v96 offset:13696
	ds_read_b128 v[56:59], v96 offset:13952
	ds_read_b128 v[60:63], v96 offset:14208
	ds_read_b128 v[64:67], v96 offset:14464
	ds_read_b32 v110, v91 offset:14720
	v_add_f32_dpp v12, v12, v12 row_half_mirror row_mask:0xf bank_mask:0xf bound_ctrl:1
	ds_read_b128 v[106:109], v96 offset:14784
	ds_read_b128 v[124:127], v96 offset:15040
	ds_read_b128 v[128:131], v96 offset:15296
	ds_read_b128 v[132:135], v96 offset:15552
	ds_read_b128 v[136:139], v96 offset:15808
	ds_read_b32 v170, v91 offset:16064
	v_add_f32_dpp v12, v12, v12 row_mirror row_mask:0xf bank_mask:0xf bound_ctrl:1
	v_pk_fma_f32 v[8:9], v[16:17], v[12:13], v[8:9] op_sel_hi:[1,0,1]
	v_pk_fma_f32 v[10:11], v[18:19], v[12:13], v[10:11] op_sel_hi:[1,0,1]
	v_pk_mul_f32 v[12:13], v[24:25], v[8:9]
	v_pk_fma_f32 v[12:13], v[26:27], v[10:11], v[12:13]
	s_nop 0
	v_add_f32_e32 v120, v12, v13
	s_waitcnt lgkmcnt(8)
	v_pk_mul_f32 v[12:13], v[32:33], v[8:9]
	v_pk_mul_f32 v[8:9], v[28:29], v[8:9]
	v_pk_fma_f32 v[12:13], v[34:35], v[10:11], v[12:13]
	v_pk_fma_f32 v[8:9], v[40:41], v[104:105], v[8:9] op_sel_hi:[1,0,1]
	v_add_f32_e32 v12, v12, v13
	v_pk_mul_f32 v[10:11], v[30:31], v[10:11]
	ds_read_b128 v[140:143], v96 offset:16128
	v_add_f32_dpp v12, v12, v12 quad_perm:[1,0,3,2] row_mask:0xf bank_mask:0xf bound_ctrl:1
	v_pk_fma_f32 v[10:11], v[42:43], v[104:105], v[10:11] op_sel_hi:[1,0,1]
	ds_read_b128 v[144:147], v96 offset:16384
	v_add_f32_dpp v12, v12, v12 quad_perm:[2,3,0,1] row_mask:0xf bank_mask:0xf bound_ctrl:1
	ds_read_b128 v[148:151], v96 offset:16640
	ds_read_b128 v[152:155], v96 offset:16896
	v_add_f32_dpp v12, v12, v12 row_half_mirror row_mask:0xf bank_mask:0xf bound_ctrl:1
	ds_read_b128 v[156:159], v96 offset:17152
	ds_read_b32 v172, v91 offset:17408
	v_add_f32_dpp v12, v12, v12 row_mirror row_mask:0xf bank_mask:0xf bound_ctrl:1
	v_pk_fma_f32 v[8:9], v[36:37], v[12:13], v[8:9] op_sel_hi:[1,0,1]
	v_pk_fma_f32 v[10:11], v[38:39], v[12:13], v[10:11] op_sel_hi:[1,0,1]
	v_pk_mul_f32 v[12:13], v[44:45], v[8:9]
	s_nop 0
	v_pk_fma_f32 v[12:13], v[46:47], v[10:11], v[12:13]
	s_nop 0
	v_add_f32_e32 v121, v12, v13
	v_pk_mul_f32 v[12:13], v[52:53], v[8:9]
	v_pk_mul_f32 v[8:9], v[48:49], v[8:9]
	v_pk_fma_f32 v[12:13], v[54:55], v[10:11], v[12:13]
	s_waitcnt lgkmcnt(12)
	v_pk_fma_f32 v[8:9], v[60:61], v[110:111], v[8:9] op_sel_hi:[1,0,1]
	v_add_f32_e32 v12, v12, v13
	v_pk_mul_f32 v[10:11], v[50:51], v[10:11]
	s_nop 0
	v_add_f32_dpp v12, v12, v12 quad_perm:[1,0,3,2] row_mask:0xf bank_mask:0xf bound_ctrl:1
	v_pk_fma_f32 v[10:11], v[62:63], v[110:111], v[10:11] op_sel_hi:[1,0,1]
	s_nop 0
	v_add_f32_dpp v12, v12, v12 quad_perm:[2,3,0,1] row_mask:0xf bank_mask:0xf bound_ctrl:1
	s_nop 1
	v_add_f32_dpp v12, v12, v12 row_half_mirror row_mask:0xf bank_mask:0xf bound_ctrl:1
	s_nop 1
	v_add_f32_dpp v12, v12, v12 row_mirror row_mask:0xf bank_mask:0xf bound_ctrl:1
	v_pk_fma_f32 v[28:29], v[56:57], v[12:13], v[8:9] op_sel_hi:[1,0,1]
	v_pk_fma_f32 v[30:31], v[58:59], v[12:13], v[10:11] op_sel_hi:[1,0,1]
	s_waitcnt lgkmcnt(6)
	v_pk_mul_f32 v[32:33], v[124:125], v[28:29]
	v_pk_mul_f32 v[8:9], v[64:65], v[28:29]
	v_pk_fma_f32 v[32:33], v[126:127], v[30:31], v[32:33]
	v_pk_mul_f32 v[28:29], v[106:107], v[28:29]
	v_add_f32_e32 v32, v32, v33
	v_pk_fma_f32 v[8:9], v[66:67], v[30:31], v[8:9]
	v_pk_fma_f32 v[28:29], v[132:133], v[170:171], v[28:29] op_sel_hi:[1,0,1]
	v_add_f32_dpp v32, v32, v32 quad_perm:[1,0,3,2] row_mask:0xf bank_mask:0xf bound_ctrl:1
	v_pk_mul_f32 v[30:31], v[108:109], v[30:31]
	v_add_f32_e32 v122, v8, v9
	v_add_f32_dpp v32, v32, v32 quad_perm:[2,3,0,1] row_mask:0xf bank_mask:0xf bound_ctrl:1
	v_pk_fma_f32 v[30:31], v[134:135], v[170:171], v[30:31] op_sel_hi:[1,0,1]
	ds_read_b128 v[16:19], v96 offset:17472
	ds_read_b128 v[24:27], v96 offset:17728
	ds_read_b128 v[12:15], v96 offset:17984
	ds_read_b128 v[20:23], v96 offset:18240
	v_add_f32_dpp v32, v32, v32 row_half_mirror row_mask:0xf bank_mask:0xf bound_ctrl:1
	ds_read_b128 v[8:11], v96 offset:18496
	ds_read_b32 v102, v91 offset:18752
	v_add_f32_dpp v32, v32, v32 row_mirror row_mask:0xf bank_mask:0xf bound_ctrl:1
	v_pk_fma_f32 v[48:49], v[128:129], v[32:33], v[28:29] op_sel_hi:[1,0,1]
	v_pk_fma_f32 v[50:51], v[130:131], v[32:33], v[30:31] op_sel_hi:[1,0,1]
	s_waitcnt lgkmcnt(6)
	v_pk_mul_f32 v[52:53], v[144:145], v[48:49]
	v_pk_mul_f32 v[28:29], v[136:137], v[48:49]
	v_pk_fma_f32 v[52:53], v[146:147], v[50:51], v[52:53]
	v_pk_mul_f32 v[48:49], v[140:141], v[48:49]
	v_add_f32_e32 v52, v52, v53
	v_pk_fma_f32 v[28:29], v[138:139], v[50:51], v[28:29]
	v_pk_fma_f32 v[48:49], v[152:153], v[172:173], v[48:49] op_sel_hi:[1,0,1]
	v_add_f32_dpp v52, v52, v52 quad_perm:[1,0,3,2] row_mask:0xf bank_mask:0xf bound_ctrl:1
	v_pk_mul_f32 v[50:51], v[142:143], v[50:51]
	v_add_f32_e32 v123, v28, v29
	v_add_f32_dpp v52, v52, v52 quad_perm:[2,3,0,1] row_mask:0xf bank_mask:0xf bound_ctrl:1
	v_pk_fma_f32 v[50:51], v[154:155], v[172:173], v[50:51] op_sel_hi:[1,0,1]
	ds_read_b128 v[36:39], v96 offset:18816
	ds_read_b128 v[44:47], v96 offset:19072
	ds_read_b128 v[32:35], v96 offset:19328
	ds_read_b128 v[40:43], v96 offset:19584
	v_add_f32_dpp v52, v52, v52 row_half_mirror row_mask:0xf bank_mask:0xf bound_ctrl:1
	ds_read_b128 v[28:31], v96 offset:19840
	ds_read_b32 v104, v91 offset:20096
	v_add_f32_dpp v52, v52, v52 row_mirror row_mask:0xf bank_mask:0xf bound_ctrl:1
	v_pk_fma_f32 v[108:109], v[148:149], v[52:53], v[48:49] op_sel_hi:[1,0,1]
	v_pk_fma_f32 v[106:107], v[150:151], v[52:53], v[50:51] op_sel_hi:[1,0,1]
	s_waitcnt lgkmcnt(6)
	v_pk_mul_f32 v[24:25], v[24:25], v[108:109]
	v_pk_mul_f32 v[16:17], v[16:17], v[108:109]
	v_pk_fma_f32 v[24:25], v[26:27], v[106:107], v[24:25]
	v_pk_fma_f32 v[16:17], v[20:21], v[102:103], v[16:17] op_sel_hi:[1,0,1]
	v_add_f32_e32 v24, v24, v25
	v_pk_mul_f32 v[18:19], v[18:19], v[106:107]
	v_pk_mul_f32 v[48:49], v[156:157], v[108:109]
	v_add_f32_dpp v20, v24, v24 quad_perm:[1,0,3,2] row_mask:0xf bank_mask:0xf bound_ctrl:1
	v_pk_fma_f32 v[18:19], v[22:23], v[102:103], v[18:19] op_sel_hi:[1,0,1]
	v_pk_fma_f32 v[48:49], v[158:159], v[106:107], v[48:49]
	v_add_f32_dpp v20, v20, v20 quad_perm:[2,3,0,1] row_mask:0xf bank_mask:0xf bound_ctrl:1
	v_add_f32_e32 v124, v48, v49
	ds_read_b128 v[56:59], v96 offset:20160
	v_add_f32_dpp v20, v20, v20 row_half_mirror row_mask:0xf bank_mask:0xf bound_ctrl:1
	ds_read_b128 v[64:67], v96 offset:20416
	ds_read_b128 v[52:55], v96 offset:20672
	v_add_f32_dpp v20, v20, v20 row_mirror row_mask:0xf bank_mask:0xf bound_ctrl:1
	v_pk_fma_f32 v[12:13], v[12:13], v[20:21], v[16:17] op_sel_hi:[1,0,1]
	v_pk_fma_f32 v[14:15], v[14:15], v[20:21], v[18:19] op_sel_hi:[1,0,1]
	v_pk_mul_f32 v[8:9], v[8:9], v[12:13]
	v_cndmask_b32_e64 v18, v115, v122, s[42:43]
	v_pk_fma_f32 v[8:9], v[10:11], v[14:15], v[8:9]
	s_waitcnt lgkmcnt(7)
	v_pk_mul_f32 v[10:11], v[38:39], v[14:15]
	v_add_f32_e32 v16, v8, v9
	v_pk_mul_f32 v[8:9], v[44:45], v[12:13]
	s_waitcnt lgkmcnt(3)
	v_pk_fma_f32 v[10:11], v[42:43], v[104:105], v[10:11] op_sel_hi:[1,0,1]
	v_pk_fma_f32 v[8:9], v[46:47], v[14:15], v[8:9]
	v_cndmask_b32_e64 v15, v113, v120, s[42:43]
	v_add_f32_e32 v17, v8, v9
	v_pk_mul_f32 v[8:9], v[36:37], v[12:13]
	v_cndmask_b32_e64 v19, v116, v123, s[42:43]
	v_add_f32_dpp v12, v17, v17 quad_perm:[1,0,3,2] row_mask:0xf bank_mask:0xf bound_ctrl:1
	v_pk_fma_f32 v[8:9], v[40:41], v[104:105], v[8:9] op_sel_hi:[1,0,1]
	v_cndmask_b32_e64 v17, v114, v121, s[42:43]
	v_add_f32_dpp v12, v12, v12 quad_perm:[2,3,0,1] row_mask:0xf bank_mask:0xf bound_ctrl:1
	v_cndmask_b32_e64 v20, v117, v124, s[42:43]
	ds_read_b128 v[60:63], v96 offset:20928
	v_add_f32_dpp v12, v12, v12 row_half_mirror row_mask:0xf bank_mask:0xf bound_ctrl:1
	ds_read_b128 v[48:51], v96 offset:21184
	ds_read_b32 v110, v91 offset:21440
	v_add_f32_dpp v12, v12, v12 row_mirror row_mask:0xf bank_mask:0xf bound_ctrl:1
	v_pk_fma_f32 v[8:9], v[32:33], v[12:13], v[8:9] op_sel_hi:[1,0,1]
	v_pk_fma_f32 v[10:11], v[34:35], v[12:13], v[10:11] op_sel_hi:[1,0,1]
	v_pk_mul_f32 v[12:13], v[28:29], v[8:9]
	s_waitcnt vmcnt(3)
	v_lshlrev_b32_e32 v28, 16, v84
	v_pk_fma_f32 v[12:13], v[30:31], v[10:11], v[12:13]
	v_and_b32_e32 v29, 0xffff0000, v84
	v_add_f32_e32 v14, v12, v13
	s_waitcnt lgkmcnt(0)
	v_pk_mul_f32 v[12:13], v[64:65], v[8:9]
	v_pk_mul_f32 v[8:9], v[56:57], v[8:9]
	v_pk_fma_f32 v[12:13], v[66:67], v[10:11], v[12:13]
	v_pk_fma_f32 v[8:9], v[60:61], v[110:111], v[8:9] op_sel_hi:[1,0,1]
	v_add_f32_e32 v12, v12, v13
	v_pk_mul_f32 v[10:11], v[58:59], v[10:11]
	s_waitcnt vmcnt(1)
	v_cvt_f32_f16_sdwa v31, v88 dst_sel:DWORD dst_unused:UNUSED_PAD src0_sel:WORD_1
	v_add_f32_dpp v12, v12, v12 quad_perm:[1,0,3,2] row_mask:0xf bank_mask:0xf bound_ctrl:1
	v_pk_fma_f32 v[10:11], v[62:63], v[110:111], v[10:11] op_sel_hi:[1,0,1]
	v_cvt_f32_f16_e32 v30, v88
	v_add_f32_dpp v12, v12, v12 quad_perm:[2,3,0,1] row_mask:0xf bank_mask:0xf bound_ctrl:1
	v_cvt_f32_f16_sdwa v35, v89 dst_sel:DWORD dst_unused:UNUSED_PAD src0_sel:WORD_1
	v_cvt_f32_f16_e32 v34, v89
	v_add_f32_dpp v12, v12, v12 row_half_mirror row_mask:0xf bank_mask:0xf bound_ctrl:1
	v_lshlrev_b32_e32 v32, 16, v85
	v_and_b32_e32 v33, 0xffff0000, v85
	v_add_f32_dpp v12, v12, v12 row_mirror row_mask:0xf bank_mask:0xf bound_ctrl:1
	v_pk_fma_f32 v[8:9], v[52:53], v[12:13], v[8:9] op_sel_hi:[1,0,1]
	v_pk_fma_f32 v[10:11], v[54:55], v[12:13], v[10:11] op_sel_hi:[1,0,1]
	v_pk_mul_f32 v[12:13], v[48:49], v[8:9]
	v_pk_mul_f32 v[22:23], v[2:3], v[32:33]
	v_pk_fma_f32 v[12:13], v[50:51], v[10:11], v[12:13]
	s_waitcnt vmcnt(0)
; DEVI void scan_item(const Params& p, int l, int item, unsigned char* smem) {
;     ...
;   constexpr int NCH = NKEY / SC_TOK;
;   SC_LOAD(0, RA);
;   SC_LOAD(1, RB);
;   SC_STAGE(0, RA);
;   __syncthreads();
;   f32x2 S01 = {0.f, 0.f}, S23 = {0.f, 0.f};
;   const int vidx = 320 + wave * 4 + rl;
;   const bool bit3 = (kl & 8) != 0, bit2 = (kl & 4) != 0, bit1 = (kl & 2) != 0, bit0 = (kl & 1) != 0;
;   __builtin_amdgcn_s_setprio(3);
;   for (int c = 0; c < NCH; c += 2) {
;     const bool more = (c + 2 < NCH);
;     if (more) SC_LOAD(c + 2, RA);
;     SC_CHUNK(0);
;     SC_STAGE(1, RB);
;     __syncthreads();
;     SC_YOUT(c, 0);
;     if (more) SC_LOAD(c + 3, RB);
	v_pk_mul_f32 v[22:23], v[90:91], v[22:23] op_sel_hi:[0,1]
	v_add_f32_e32 v12, v12, v13
	v_cndmask_b32_e64 v13, v120, v113, s[42:43]
	v_pk_mul_f32 v[26:27], v[34:35], v[22:23] neg_lo:[0,1] neg_hi:[0,1]
	v_pk_add_f32 v[34:35], v[34:35], -1.0 op_sel_hi:[1,0]
	v_add_f32_dpp v13, v15, v13 row_ror:8 row_mask:0xf bank_mask:0xf bound_ctrl:1
	v_cndmask_b32_e64 v15, v121, v114, s[42:43]
	v_pk_fma_f32 v[34:35], v[6:7], v[34:35], 1.0 op_sel_hi:[1,1,0]
	s_nop 0
	v_add_f32_dpp v15, v17, v15 row_ror:8 row_mask:0xf bank_mask:0xf bound_ctrl:1
	v_cndmask_b32_e64 v17, v122, v115, s[42:43]
	s_nop 1
	v_add_f32_dpp v17, v18, v17 row_ror:8 row_mask:0xf bank_mask:0xf bound_ctrl:1
	v_cndmask_b32_e64 v18, v123, v116, s[42:43]
	s_nop 1
	v_add_f32_dpp v18, v19, v18 row_ror:8 row_mask:0xf bank_mask:0xf bound_ctrl:1
	v_cndmask_b32_e64 v19, v124, v117, s[42:43]
	s_nop 1
	v_add_f32_dpp v19, v20, v19 row_ror:8 row_mask:0xf bank_mask:0xf bound_ctrl:1
	v_cndmask_b32_e64 v20, v16, v111, s[42:43]
	v_cndmask_b32_e64 v16, v111, v16, s[42:43]
	s_nop 1
	v_add_f32_dpp v16, v16, v20 row_ror:8 row_mask:0xf bank_mask:0xf bound_ctrl:1
	v_cndmask_b32_e64 v20, v14, v118, s[42:43]
	v_cndmask_b32_e64 v14, v118, v14, s[42:43]
	s_nop 1
	v_add_f32_dpp v14, v14, v20 row_ror:8 row_mask:0xf bank_mask:0xf bound_ctrl:1
	v_cndmask_b32_e64 v20, v12, v119, s[42:43]
	v_cndmask_b32_e64 v12, v119, v12, s[42:43]
	s_nop 1
	v_add_f32_dpp v12, v12, v20 row_ror:8 row_mask:0xf bank_mask:0xf bound_ctrl:1
	v_cndmask_b32_e64 v20, v19, v13, s[44:45]
	v_cndmask_b32_e64 v13, v13, v19, s[44:45]
	v_cndmask_b32_e64 v19, v16, v15, s[44:45]
	v_cndmask_b32_e64 v15, v15, v16, s[44:45]
	v_cndmask_b32_e64 v16, v14, v17, s[44:45]
	v_cndmask_b32_e64 v14, v17, v14, s[44:45]
	v_add_f32_dpp v13, v13, v20 row_half_mirror row_mask:0xf bank_mask:0xf bound_ctrl:1
	v_add_f32_dpp v15, v15, v19 row_half_mirror row_mask:0xf bank_mask:0xf bound_ctrl:1
	v_add_f32_dpp v14, v14, v16 row_half_mirror row_mask:0xf bank_mask:0xf bound_ctrl:1
	v_cndmask_b32_e64 v16, v12, v18, s[44:45]
	v_cndmask_b32_e64 v12, v18, v12, s[44:45]
	v_pk_mul_f32 v[18:19], v[0:1], v[28:29]
	v_cvt_f32_f16_sdwa v17, v86 dst_sel:DWORD dst_unused:UNUSED_PAD src0_sel:WORD_1
	v_add_f32_dpp v12, v12, v16 row_half_mirror row_mask:0xf bank_mask:0xf bound_ctrl:1
	v_cndmask_b32_e64 v16, v14, v13, s[46:47]
	v_cndmask_b32_e64 v13, v13, v14, s[46:47]
	v_pk_mul_f32 v[20:21], v[90:91], v[18:19] op_sel_hi:[0,1]
	v_cvt_f32_f16_e32 v18, v87
	v_add_f32_dpp v13, v13, v16 quad_perm:[2,3,0,1] row_mask:0xf bank_mask:0xf bound_ctrl:1
	v_cvt_f32_f16_e32 v16, v86
	v_cvt_f32_f16_sdwa v19, v87 dst_sel:DWORD dst_unused:UNUSED_PAD src0_sel:WORD_1
	v_mul_f32_e32 v17, 0x3fb8aa3b, v17
	v_mul_f32_e32 v18, 0x3fb8aa3b, v18
	v_mul_f32_e32 v16, 0x3fb8aa3b, v16
	v_mul_f32_e32 v19, 0x3fb8aa3b, v19
	v_cndmask_b32_e64 v14, v12, v15, s[46:47]
	v_cndmask_b32_e64 v12, v15, v12, s[46:47]
	v_exp_f32_e32 v16, v16
	v_exp_f32_e32 v17, v17
	v_exp_f32_e32 v18, v18
	v_exp_f32_e32 v19, v19
	v_add_f32_dpp v12, v12, v14 quad_perm:[2,3,0,1] row_mask:0xf bank_mask:0xf bound_ctrl:1
	v_cndmask_b32_e64 v14, v12, v13, s[48:49]
	v_cndmask_b32_e64 v12, v13, v12, s[48:49]
	v_pk_mul_f32 v[24:25], v[30:31], v[20:21] neg_lo:[0,1] neg_hi:[0,1]
	v_pk_add_f32 v[30:31], v[30:31], -1.0 op_sel_hi:[1,0]
	v_add_f32_dpp v12, v12, v14 quad_perm:[1,0,3,2] row_mask:0xf bank_mask:0xf bound_ctrl:1
	v_pk_fma_f32 v[36:37], v[4:5], v[30:31], 1.0 op_sel_hi:[1,1,0]
	ds_write_b32 v97, v12 offset:43008
	v_lshlrev_b32_e32 v12, 16, v82
	v_and_b32_e32 v13, 0xffff0000, v82
	v_lshlrev_b32_e32 v14, 16, v83
	v_and_b32_e32 v15, 0xffff0000, v83
	v_pk_mul_f32 v[30:31], v[34:35], v[32:33]
	v_pk_mul_f32 v[28:29], v[36:37], v[28:29]
	ds_write_b128 v98, v[16:19]
	ds_write_b128 v98, v[20:23] offset:256
	ds_write_b128 v98, v[24:27] offset:512
	ds_write_b128 v98, v[28:31] offset:768
	ds_write_b128 v98, v[12:15] offset:1024
	s_and_saveexec_b64 s[50:51], s[40:41]
	v_lshlrev_b32_e32 v12, 16, v80
	v_and_b32_e32 v13, 0xffff0000, v80
	v_lshlrev_b32_e32 v14, 16, v81
	v_and_b32_e32 v15, 0xffff0000, v81
	ds_write_b128 v98, v[12:15] offset:1280
	s_or_b64 exec, exec, s[50:51]
	v_subrev_u32_e32 v12, 48, v112
	v_cmp_gt_i32_e32 vcc, s92, v12
	v_add_u32_e32 v13, 0xfffffed0, v112
	v_mov_b32_e32 v15, s36
	v_cndmask_b32_e32 v14, v226, v227, vcc
	v_cndmask_b32_e32 v12, v13, v12, vcc
	v_mov_b32_e32 v13, s27
	v_add_u32_e32 v14, v14, v105
	v_cndmask_b32_e32 v13, v13, v15, vcc
	v_cndmask_b32_e64 v12, v14, v12, s[38:39]
	s_waitcnt lgkmcnt(0)
	s_barrier
	v_add_u32_e32 v12, v12, v13
	ds_read_b32 v13, v99 offset:43008
	s_mov_b32 s2, 0x3d800000
	s_andn2_b64 vcc, exec, s[90:91]
	s_waitcnt lgkmcnt(0)
	v_fma_mixlo_f16 v14, v13, s2, 0
	v_ashrrev_i32_e32 v13, 31, v12
	v_lshlrev_b64 v[12:13], 10, v[12:13]
	v_lshl_add_u64 v[12:13], v[100:101], 0, v[12:13]
	global_store_short v[12:13], v14, off
	v_cndmask_b32_e64 v12, 0, 1, s[90:91]
	v_cmp_ne_u32_e64 s[50:51], 1, v12
	s_cbranch_vccnz .LBB0_205
	v_cmp_gt_i32_e32 vcc, s92, v112
	v_add_u32_e32 v12, 0xffffff00, v112
	s_movk_i32 s2, 0xffd0
	v_cndmask_b32_e32 v13, v226, v227, vcc
	v_cndmask_b32_e32 v12, v12, v112, vcc
	v_mov_b32_e32 v14, s27
	v_mov_b32_e32 v15, s36
	v_add3_u32 v13, v13, v105, s2
	v_cndmask_b32_e32 v14, v14, v15, vcc
	v_cndmask_b32_e64 v12, v13, v12, s[38:39]
	v_add_u32_e32 v12, v12, v14
	v_mov_b64_e32 v[14:15], s[22:23]
	v_mad_i64_i32 v[14:15], s[90:91], v12, s3, v[14:15]
	v_lshl_add_u64 v[16:17], v[14:15], 0, v[162:163]
	global_load_dwordx2 v[82:83], v[16:17], off
	global_load_dwordx2 v[84:85], v[16:17], off offset:1024
	s_and_saveexec_b64 s[90:91], s[40:41]
	s_cbranch_execz .LBB0_204
	s_lshl_b32 s96, s26, 1
	v_lshl_add_u64 v[14:15], v[14:15], 0, s[96:97]
	v_lshl_add_u64 v[14:15], v[14:15], 0, v[162:163]
	global_load_dwordx2 v[80:81], v[14:15], off offset:2048

.LBB0_205:
	ds_read_b128 v[12:15], v103 offset:21504
	ds_read_b128 v[16:19], v103 offset:21760
	ds_read_b128 v[20:23], v103 offset:22016
	ds_read_b128 v[24:27], v103 offset:22272
	ds_read_b128 v[28:31], v103 offset:22528
	ds_read_b32 v102, v91 offset:22784
	ds_read_b128 v[32:35], v103 offset:22848
	ds_read_b128 v[36:39], v103 offset:23104
	ds_read_b128 v[40:43], v103 offset:23360
	ds_read_b128 v[44:47], v103 offset:23616
	ds_read_b128 v[48:51], v103 offset:23872
	ds_read_b32 v104, v91 offset:24128
	ds_read_b128 v[52:55], v103 offset:24192
	ds_read_b128 v[56:59], v103 offset:24448
	ds_read_b128 v[60:63], v103 offset:24704
	ds_read_b128 v[64:67], v103 offset:24960
	ds_read_b128 v[106:109], v103 offset:25216
	ds_read_b32 v110, v91 offset:25472
	s_waitcnt lgkmcnt(14)
	v_pk_mul_f32 v[16:17], v[8:9], v[16:17]
	s_and_b64 vcc, exec, s[50:51]
	v_pk_fma_f32 v[16:17], v[10:11], v[18:19], v[16:17]
	s_waitcnt lgkmcnt(12)
	v_pk_mul_f32 v[18:19], v[26:27], v[102:103] op_sel_hi:[1,0]
	v_add_f32_e32 v111, v16, v17
	v_pk_mul_f32 v[16:17], v[24:25], v[102:103] op_sel_hi:[1,0]
	v_pk_fma_f32 v[10:11], v[10:11], v[14:15], v[18:19]
	v_pk_fma_f32 v[8:9], v[8:9], v[12:13], v[16:17]
	v_add_f32_dpp v12, v111, v111 quad_perm:[1,0,3,2] row_mask:0xf bank_mask:0xf bound_ctrl:1
	s_nop 1
	v_add_f32_dpp v12, v12, v12 quad_perm:[2,3,0,1] row_mask:0xf bank_mask:0xf bound_ctrl:1
	s_nop 1
	v_add_f32_dpp v12, v12, v12 row_half_mirror row_mask:0xf bank_mask:0xf bound_ctrl:1
	s_nop 1
	v_add_f32_dpp v12, v12, v12 row_mirror row_mask:0xf bank_mask:0xf bound_ctrl:1
	v_pk_fma_f32 v[8:9], v[20:21], v[12:13], v[8:9] op_sel_hi:[1,0,1]
	v_pk_fma_f32 v[10:11], v[22:23], v[12:13], v[10:11] op_sel_hi:[1,0,1]
	v_pk_mul_f32 v[12:13], v[28:29], v[8:9]
	s_nop 0
	v_pk_fma_f32 v[12:13], v[30:31], v[10:11], v[12:13]
	v_add_f32_e32 v113, v12, v13
	s_waitcnt lgkmcnt(6)
	v_pk_mul_f32 v[12:13], v[36:37], v[8:9]
	v_pk_mul_f32 v[8:9], v[32:33], v[8:9]
	v_pk_fma_f32 v[12:13], v[38:39], v[10:11], v[12:13]
	v_pk_fma_f32 v[8:9], v[44:45], v[104:105], v[8:9] op_sel_hi:[1,0,1]
	v_add_f32_e32 v12, v12, v13
	v_pk_mul_f32 v[10:11], v[34:35], v[10:11]
	ds_read_b128 v[28:31], v103 offset:25536
	v_add_f32_dpp v12, v12, v12 quad_perm:[1,0,3,2] row_mask:0xf bank_mask:0xf bound_ctrl:1
	v_pk_fma_f32 v[10:11], v[46:47], v[104:105], v[10:11] op_sel_hi:[1,0,1]
	ds_read_b128 v[116:119], v103 offset:25792
	v_add_f32_dpp v12, v12, v12 quad_perm:[2,3,0,1] row_mask:0xf bank_mask:0xf bound_ctrl:1
	ds_read_b128 v[120:123], v103 offset:26048
	ds_read_b128 v[124:127], v103 offset:26304
	v_add_f32_dpp v12, v12, v12 row_half_mirror row_mask:0xf bank_mask:0xf bound_ctrl:1
	ds_read_b128 v[128:131], v103 offset:26560
	ds_read_b32 v148, v91 offset:26816
	v_add_f32_dpp v12, v12, v12 row_mirror row_mask:0xf bank_mask:0xf bound_ctrl:1
	v_pk_fma_f32 v[8:9], v[40:41], v[12:13], v[8:9] op_sel_hi:[1,0,1]
	v_pk_fma_f32 v[10:11], v[42:43], v[12:13], v[10:11] op_sel_hi:[1,0,1]
	v_pk_mul_f32 v[12:13], v[48:49], v[8:9]
	s_nop 0
	v_pk_fma_f32 v[12:13], v[50:51], v[10:11], v[12:13]
	v_add_f32_e32 v114, v12, v13
	s_waitcnt lgkmcnt(6)
	v_pk_mul_f32 v[12:13], v[56:57], v[8:9]
	v_pk_mul_f32 v[8:9], v[52:53], v[8:9]
	v_pk_fma_f32 v[12:13], v[58:59], v[10:11], v[12:13]
	v_pk_fma_f32 v[8:9], v[64:65], v[110:111], v[8:9] op_sel_hi:[1,0,1]
	v_add_f32_e32 v12, v12, v13
	v_pk_mul_f32 v[10:11], v[54:55], v[10:11]
	ds_read_b128 v[48:51], v103 offset:26880
	v_add_f32_dpp v12, v12, v12 quad_perm:[1,0,3,2] row_mask:0xf bank_mask:0xf bound_ctrl:1
	v_pk_fma_f32 v[10:11], v[66:67], v[110:111], v[10:11] op_sel_hi:[1,0,1]
	ds_read_b128 v[132:135], v103 offset:27136
	v_add_f32_dpp v12, v12, v12 quad_perm:[2,3,0,1] row_mask:0xf bank_mask:0xf bound_ctrl:1
	ds_read_b128 v[136:139], v103 offset:27392
	ds_read_b128 v[140:143], v103 offset:27648
	v_add_f32_dpp v12, v12, v12 row_half_mirror row_mask:0xf bank_mask:0xf bound_ctrl:1
	ds_read_b128 v[144:147], v103 offset:27904
	ds_read_b32 v150, v91 offset:28160
	v_add_f32_dpp v12, v12, v12 row_mirror row_mask:0xf bank_mask:0xf bound_ctrl:1
	v_pk_fma_f32 v[32:33], v[60:61], v[12:13], v[8:9] op_sel_hi:[1,0,1]
	v_pk_fma_f32 v[34:35], v[62:63], v[12:13], v[10:11] op_sel_hi:[1,0,1]
	s_waitcnt lgkmcnt(6)
	v_pk_mul_f32 v[36:37], v[116:117], v[32:33]
	v_pk_mul_f32 v[8:9], v[106:107], v[32:33]
	v_pk_fma_f32 v[36:37], v[118:119], v[34:35], v[36:37]
	v_pk_mul_f32 v[28:29], v[28:29], v[32:33]
	v_add_f32_e32 v36, v36, v37
	v_pk_fma_f32 v[28:29], v[124:125], v[148:149], v[28:29] op_sel_hi:[1,0,1]
	v_pk_mul_f32 v[30:31], v[30:31], v[34:35]
	v_add_f32_dpp v32, v36, v36 quad_perm:[1,0,3,2] row_mask:0xf bank_mask:0xf bound_ctrl:1
	v_pk_fma_f32 v[30:31], v[126:127], v[148:149], v[30:31] op_sel_hi:[1,0,1]
	v_pk_fma_f32 v[8:9], v[108:109], v[34:35], v[8:9]
	v_add_f32_dpp v32, v32, v32 quad_perm:[2,3,0,1] row_mask:0xf bank_mask:0xf bound_ctrl:1
	v_add_f32_e32 v115, v8, v9
	ds_read_b128 v[16:19], v103 offset:28224
	ds_read_b128 v[24:27], v103 offset:28480
	ds_read_b128 v[12:15], v103 offset:28736
	ds_read_b128 v[20:23], v103 offset:28992
	v_add_f32_dpp v32, v32, v32 row_half_mirror row_mask:0xf bank_mask:0xf bound_ctrl:1
	ds_read_b128 v[8:11], v103 offset:29248
	ds_read_b32 v102, v91 offset:29504
	v_add_f32_dpp v32, v32, v32 row_mirror row_mask:0xf bank_mask:0xf bound_ctrl:1
	v_pk_fma_f32 v[52:53], v[120:121], v[32:33], v[28:29] op_sel_hi:[1,0,1]
	v_pk_fma_f32 v[54:55], v[122:123], v[32:33], v[30:31] op_sel_hi:[1,0,1]
	s_waitcnt lgkmcnt(6)
	v_pk_mul_f32 v[56:57], v[132:133], v[52:53]
	v_pk_mul_f32 v[28:29], v[128:129], v[52:53]
	v_pk_fma_f32 v[56:57], v[134:135], v[54:55], v[56:57]
	v_pk_mul_f32 v[48:49], v[48:49], v[52:53]
	v_add_f32_e32 v56, v56, v57
	v_pk_fma_f32 v[48:49], v[140:141], v[150:151], v[48:49] op_sel_hi:[1,0,1]
	v_pk_mul_f32 v[50:51], v[50:51], v[54:55]
	v_add_f32_dpp v52, v56, v56 quad_perm:[1,0,3,2] row_mask:0xf bank_mask:0xf bound_ctrl:1
	v_pk_fma_f32 v[50:51], v[142:143], v[150:151], v[50:51] op_sel_hi:[1,0,1]
	v_pk_fma_f32 v[28:29], v[130:131], v[54:55], v[28:29]
	v_add_f32_dpp v52, v52, v52 quad_perm:[2,3,0,1] row_mask:0xf bank_mask:0xf bound_ctrl:1
	v_add_f32_e32 v116, v28, v29
	ds_read_b128 v[36:39], v103 offset:29568
	ds_read_b128 v[44:47], v103 offset:29824
	ds_read_b128 v[32:35], v103 offset:30080
	ds_read_b128 v[40:43], v103 offset:30336
	v_add_f32_dpp v52, v52, v52 row_half_mirror row_mask:0xf bank_mask:0xf bound_ctrl:1
	ds_read_b128 v[28:31], v103 offset:30592
	ds_read_b32 v104, v91 offset:30848
	v_add_f32_dpp v52, v52, v52 row_mirror row_mask:0xf bank_mask:0xf bound_ctrl:1
	v_pk_fma_f32 v[110:111], v[136:137], v[52:53], v[48:49] op_sel_hi:[1,0,1]
	v_pk_fma_f32 v[108:109], v[138:139], v[52:53], v[50:51] op_sel_hi:[1,0,1]
	s_waitcnt lgkmcnt(6)
	v_pk_mul_f32 v[24:25], v[24:25], v[110:111]
	v_pk_mul_f32 v[16:17], v[16:17], v[110:111]
	v_pk_fma_f32 v[24:25], v[26:27], v[108:109], v[24:25]
	v_pk_fma_f32 v[16:17], v[20:21], v[102:103], v[16:17] op_sel_hi:[1,0,1]
	v_add_f32_e32 v24, v24, v25
	v_pk_mul_f32 v[48:49], v[144:145], v[110:111]
	v_pk_mul_f32 v[18:19], v[18:19], v[108:109]
	v_add_f32_dpp v20, v24, v24 quad_perm:[1,0,3,2] row_mask:0xf bank_mask:0xf bound_ctrl:1
	v_pk_fma_f32 v[48:49], v[146:147], v[108:109], v[48:49]
	v_pk_fma_f32 v[18:19], v[22:23], v[102:103], v[18:19] op_sel_hi:[1,0,1]
	v_add_f32_dpp v20, v20, v20 quad_perm:[2,3,0,1] row_mask:0xf bank_mask:0xf bound_ctrl:1
	v_add_f32_e32 v117, v48, v49
	ds_read_b128 v[56:59], v103 offset:30912
	ds_read_b128 v[64:67], v103 offset:31168
	ds_read_b128 v[52:55], v103 offset:31424
	ds_read_b128 v[60:63], v103 offset:31680
	v_add_f32_dpp v20, v20, v20 row_half_mirror row_mask:0xf bank_mask:0xf bound_ctrl:1
	ds_read_b128 v[48:51], v103 offset:31936
	ds_read_b32 v106, v91 offset:32192
	v_add_f32_dpp v20, v20, v20 row_mirror row_mask:0xf bank_mask:0xf bound_ctrl:1
	v_pk_fma_f32 v[108:109], v[12:13], v[20:21], v[16:17] op_sel_hi:[1,0,1]
	v_pk_fma_f32 v[118:119], v[14:15], v[20:21], v[18:19] op_sel_hi:[1,0,1]
	s_waitcnt lgkmcnt(6)
	v_pk_mul_f32 v[44:45], v[44:45], v[108:109]
	v_pk_mul_f32 v[36:37], v[36:37], v[108:109]
	v_pk_fma_f32 v[44:45], v[46:47], v[118:119], v[44:45]
	v_pk_fma_f32 v[36:37], v[40:41], v[104:105], v[36:37] op_sel_hi:[1,0,1]
	v_add_f32_e32 v44, v44, v45
	v_pk_mul_f32 v[38:39], v[38:39], v[118:119]
	v_pk_mul_f32 v[8:9], v[8:9], v[108:109]
	v_add_f32_dpp v40, v44, v44 quad_perm:[1,0,3,2] row_mask:0xf bank_mask:0xf bound_ctrl:1
	v_pk_fma_f32 v[38:39], v[42:43], v[104:105], v[38:39] op_sel_hi:[1,0,1]
	v_pk_fma_f32 v[8:9], v[10:11], v[118:119], v[8:9]
	v_add_f32_dpp v40, v40, v40 quad_perm:[2,3,0,1] row_mask:0xf bank_mask:0xf bound_ctrl:1
	v_add_f32_e32 v111, v8, v9
	ds_read_b128 v[8:11], v103 offset:32256
	ds_read_b128 v[12:15], v103 offset:32512
	ds_read_b128 v[16:19], v103 offset:32768
	ds_read_b128 v[20:23], v103 offset:33024
	v_add_f32_dpp v40, v40, v40 row_half_mirror row_mask:0xf bank_mask:0xf bound_ctrl:1
	ds_read_b128 v[24:27], v103 offset:33280
	ds_read_b32 v102, v91 offset:33536
	v_add_f32_dpp v40, v40, v40 row_mirror row_mask:0xf bank_mask:0xf bound_ctrl:1
	v_pk_fma_f32 v[108:109], v[32:33], v[40:41], v[36:37] op_sel_hi:[1,0,1]
	v_pk_fma_f32 v[120:121], v[34:35], v[40:41], v[38:39] op_sel_hi:[1,0,1]
	s_waitcnt lgkmcnt(6)
	v_pk_mul_f32 v[64:65], v[64:65], v[108:109]
	v_pk_mul_f32 v[56:57], v[56:57], v[108:109]
	v_pk_fma_f32 v[64:65], v[66:67], v[120:121], v[64:65]
	v_pk_fma_f32 v[56:57], v[60:61], v[106:107], v[56:57] op_sel_hi:[1,0,1]
	v_add_f32_e32 v64, v64, v65
	v_pk_mul_f32 v[58:59], v[58:59], v[120:121]
	v_pk_mul_f32 v[28:29], v[28:29], v[108:109]
	v_add_f32_dpp v60, v64, v64 quad_perm:[1,0,3,2] row_mask:0xf bank_mask:0xf bound_ctrl:1
	v_pk_fma_f32 v[58:59], v[62:63], v[106:107], v[58:59] op_sel_hi:[1,0,1]
	v_pk_fma_f32 v[28:29], v[30:31], v[120:121], v[28:29]
	v_add_f32_dpp v60, v60, v60 quad_perm:[2,3,0,1] row_mask:0xf bank_mask:0xf bound_ctrl:1
	v_add_f32_e32 v118, v28, v29
	ds_read_b128 v[28:31], v103 offset:33600
	ds_read_b128 v[32:35], v103 offset:33856
	ds_read_b128 v[36:39], v103 offset:34112
	ds_read_b128 v[40:43], v103 offset:34368
	v_add_f32_dpp v60, v60, v60 row_half_mirror row_mask:0xf bank_mask:0xf bound_ctrl:1
	ds_read_b128 v[44:47], v103 offset:34624
	ds_read_b32 v104, v91 offset:34880
	v_add_f32_dpp v60, v60, v60 row_mirror row_mask:0xf bank_mask:0xf bound_ctrl:1
	v_pk_fma_f32 v[106:107], v[52:53], v[60:61], v[56:57] op_sel_hi:[1,0,1]
	v_pk_fma_f32 v[108:109], v[54:55], v[60:61], v[58:59] op_sel_hi:[1,0,1]
	s_waitcnt lgkmcnt(6)
	v_pk_mul_f32 v[12:13], v[12:13], v[106:107]
	v_pk_mul_f32 v[8:9], v[8:9], v[106:107]
	v_pk_fma_f32 v[12:13], v[14:15], v[108:109], v[12:13]
	v_pk_fma_f32 v[8:9], v[20:21], v[102:103], v[8:9] op_sel_hi:[1,0,1]
	v_add_f32_e32 v12, v12, v13
	v_pk_mul_f32 v[10:11], v[10:11], v[108:109]
	v_pk_mul_f32 v[48:49], v[48:49], v[106:107]
	v_add_f32_dpp v12, v12, v12 quad_perm:[1,0,3,2] row_mask:0xf bank_mask:0xf bound_ctrl:1
	v_pk_fma_f32 v[10:11], v[22:23], v[102:103], v[10:11] op_sel_hi:[1,0,1]
	v_pk_fma_f32 v[48:49], v[50:51], v[108:109], v[48:49]
	v_add_f32_dpp v12, v12, v12 quad_perm:[2,3,0,1] row_mask:0xf bank_mask:0xf bound_ctrl:1
	v_add_f32_e32 v119, v48, v49
	ds_read_b128 v[48:51], v103 offset:34944
	ds_read_b128 v[52:55], v103 offset:35200
	ds_read_b128 v[56:59], v103 offset:35456
	ds_read_b128 v[60:63], v103 offset:35712
	ds_read_b128 v[64:67], v103 offset:35968
	ds_read_b32 v110, v91 offset:36224
	v_add_f32_dpp v12, v12, v12 row_half_mirror row_mask:0xf bank_mask:0xf bound_ctrl:1
	ds_read_b128 v[106:109], v103 offset:36288
	ds_read_b128 v[124:127], v103 offset:36544
	ds_read_b128 v[128:131], v103 offset:36800
	ds_read_b128 v[132:135], v103 offset:37056
	ds_read_b128 v[136:139], v103 offset:37312
	ds_read_b32 v170, v91 offset:37568
	v_add_f32_dpp v12, v12, v12 row_mirror row_mask:0xf bank_mask:0xf bound_ctrl:1
	v_pk_fma_f32 v[8:9], v[16:17], v[12:13], v[8:9] op_sel_hi:[1,0,1]
	v_pk_fma_f32 v[10:11], v[18:19], v[12:13], v[10:11] op_sel_hi:[1,0,1]
	v_pk_mul_f32 v[12:13], v[24:25], v[8:9]
	v_pk_fma_f32 v[12:13], v[26:27], v[10:11], v[12:13]
	s_nop 0
	v_add_f32_e32 v120, v12, v13
	s_waitcnt lgkmcnt(8)
	v_pk_mul_f32 v[12:13], v[32:33], v[8:9]
	v_pk_mul_f32 v[8:9], v[28:29], v[8:9]
	v_pk_fma_f32 v[12:13], v[34:35], v[10:11], v[12:13]
	v_pk_fma_f32 v[8:9], v[40:41], v[104:105], v[8:9] op_sel_hi:[1,0,1]
	v_add_f32_e32 v12, v12, v13
	v_pk_mul_f32 v[10:11], v[30:31], v[10:11]
	ds_read_b128 v[140:143], v103 offset:37632
	v_add_f32_dpp v12, v12, v12 quad_perm:[1,0,3,2] row_mask:0xf bank_mask:0xf bound_ctrl:1
	v_pk_fma_f32 v[10:11], v[42:43], v[104:105], v[10:11] op_sel_hi:[1,0,1]
	ds_read_b128 v[144:147], v103 offset:37888
	v_add_f32_dpp v12, v12, v12 quad_perm:[2,3,0,1] row_mask:0xf bank_mask:0xf bound_ctrl:1
	ds_read_b128 v[148:151], v103 offset:38144
	ds_read_b128 v[152:155], v103 offset:38400
	v_add_f32_dpp v12, v12, v12 row_half_mirror row_mask:0xf bank_mask:0xf bound_ctrl:1
	ds_read_b128 v[156:159], v103 offset:38656
	ds_read_b32 v172, v91 offset:38912
	v_add_f32_dpp v12, v12, v12 row_mirror row_mask:0xf bank_mask:0xf bound_ctrl:1
	v_pk_fma_f32 v[8:9], v[36:37], v[12:13], v[8:9] op_sel_hi:[1,0,1]
	v_pk_fma_f32 v[10:11], v[38:39], v[12:13], v[10:11] op_sel_hi:[1,0,1]
	v_pk_mul_f32 v[12:13], v[44:45], v[8:9]
	s_nop 0
	v_pk_fma_f32 v[12:13], v[46:47], v[10:11], v[12:13]
	s_nop 0
	v_add_f32_e32 v121, v12, v13
	v_pk_mul_f32 v[12:13], v[52:53], v[8:9]
	v_pk_mul_f32 v[8:9], v[48:49], v[8:9]
	v_pk_fma_f32 v[12:13], v[54:55], v[10:11], v[12:13]
	s_waitcnt lgkmcnt(12)
	v_pk_fma_f32 v[8:9], v[60:61], v[110:111], v[8:9] op_sel_hi:[1,0,1]
	v_add_f32_e32 v12, v12, v13
	v_pk_mul_f32 v[10:11], v[50:51], v[10:11]
	s_nop 0
	v_add_f32_dpp v12, v12, v12 quad_perm:[1,0,3,2] row_mask:0xf bank_mask:0xf bound_ctrl:1
	v_pk_fma_f32 v[10:11], v[62:63], v[110:111], v[10:11] op_sel_hi:[1,0,1]
	s_nop 0
	v_add_f32_dpp v12, v12, v12 quad_perm:[2,3,0,1] row_mask:0xf bank_mask:0xf bound_ctrl:1
	s_nop 1
	v_add_f32_dpp v12, v12, v12 row_half_mirror row_mask:0xf bank_mask:0xf bound_ctrl:1
	s_nop 1
	v_add_f32_dpp v12, v12, v12 row_mirror row_mask:0xf bank_mask:0xf bound_ctrl:1
	v_pk_fma_f32 v[28:29], v[56:57], v[12:13], v[8:9] op_sel_hi:[1,0,1]
	v_pk_fma_f32 v[30:31], v[58:59], v[12:13], v[10:11] op_sel_hi:[1,0,1]
	s_waitcnt lgkmcnt(6)
	v_pk_mul_f32 v[32:33], v[124:125], v[28:29]
	v_pk_mul_f32 v[8:9], v[64:65], v[28:29]
	v_pk_fma_f32 v[32:33], v[126:127], v[30:31], v[32:33]
	v_pk_mul_f32 v[28:29], v[106:107], v[28:29]
	v_add_f32_e32 v32, v32, v33
	v_pk_fma_f32 v[8:9], v[66:67], v[30:31], v[8:9]
	v_pk_fma_f32 v[28:29], v[132:133], v[170:171], v[28:29] op_sel_hi:[1,0,1]
	v_add_f32_dpp v32, v32, v32 quad_perm:[1,0,3,2] row_mask:0xf bank_mask:0xf bound_ctrl:1
	v_pk_mul_f32 v[30:31], v[108:109], v[30:31]
	v_add_f32_e32 v122, v8, v9
	v_add_f32_dpp v32, v32, v32 quad_perm:[2,3,0,1] row_mask:0xf bank_mask:0xf bound_ctrl:1
	v_pk_fma_f32 v[30:31], v[134:135], v[170:171], v[30:31] op_sel_hi:[1,0,1]
	ds_read_b128 v[16:19], v103 offset:38976
	ds_read_b128 v[24:27], v103 offset:39232
	ds_read_b128 v[12:15], v103 offset:39488
	ds_read_b128 v[20:23], v103 offset:39744
	v_add_f32_dpp v32, v32, v32 row_half_mirror row_mask:0xf bank_mask:0xf bound_ctrl:1
	ds_read_b128 v[8:11], v103 offset:40000
	ds_read_b32 v102, v91 offset:40256
	v_add_f32_dpp v32, v32, v32 row_mirror row_mask:0xf bank_mask:0xf bound_ctrl:1
	v_pk_fma_f32 v[48:49], v[128:129], v[32:33], v[28:29] op_sel_hi:[1,0,1]
	v_pk_fma_f32 v[50:51], v[130:131], v[32:33], v[30:31] op_sel_hi:[1,0,1]
	s_waitcnt lgkmcnt(6)
	v_pk_mul_f32 v[52:53], v[144:145], v[48:49]
	v_pk_mul_f32 v[28:29], v[136:137], v[48:49]
	v_pk_fma_f32 v[52:53], v[146:147], v[50:51], v[52:53]
	v_pk_mul_f32 v[48:49], v[140:141], v[48:49]
	v_add_f32_e32 v52, v52, v53
	v_pk_fma_f32 v[28:29], v[138:139], v[50:51], v[28:29]
	v_pk_fma_f32 v[48:49], v[152:153], v[172:173], v[48:49] op_sel_hi:[1,0,1]
	v_add_f32_dpp v52, v52, v52 quad_perm:[1,0,3,2] row_mask:0xf bank_mask:0xf bound_ctrl:1
	v_pk_mul_f32 v[50:51], v[142:143], v[50:51]
	v_add_f32_e32 v123, v28, v29
	v_add_f32_dpp v52, v52, v52 quad_perm:[2,3,0,1] row_mask:0xf bank_mask:0xf bound_ctrl:1
	v_pk_fma_f32 v[50:51], v[154:155], v[172:173], v[50:51] op_sel_hi:[1,0,1]
	ds_read_b128 v[36:39], v103 offset:40320
	ds_read_b128 v[44:47], v103 offset:40576
	ds_read_b128 v[32:35], v103 offset:40832
	ds_read_b128 v[40:43], v103 offset:41088
	v_add_f32_dpp v52, v52, v52 row_half_mirror row_mask:0xf bank_mask:0xf bound_ctrl:1
	ds_read_b128 v[28:31], v103 offset:41344
	ds_read_b32 v104, v91 offset:41600
	v_add_f32_dpp v52, v52, v52 row_mirror row_mask:0xf bank_mask:0xf bound_ctrl:1
	v_pk_fma_f32 v[108:109], v[148:149], v[52:53], v[48:49] op_sel_hi:[1,0,1]
	v_pk_fma_f32 v[106:107], v[150:151], v[52:53], v[50:51] op_sel_hi:[1,0,1]
	s_waitcnt lgkmcnt(6)
	v_pk_mul_f32 v[24:25], v[24:25], v[108:109]
	v_pk_mul_f32 v[16:17], v[16:17], v[108:109]
	v_pk_fma_f32 v[24:25], v[26:27], v[106:107], v[24:25]
	v_pk_fma_f32 v[16:17], v[20:21], v[102:103], v[16:17] op_sel_hi:[1,0,1]
	v_add_f32_e32 v24, v24, v25
	v_pk_mul_f32 v[18:19], v[18:19], v[106:107]
	v_pk_mul_f32 v[48:49], v[156:157], v[108:109]
	v_add_f32_dpp v20, v24, v24 quad_perm:[1,0,3,2] row_mask:0xf bank_mask:0xf bound_ctrl:1
	v_pk_fma_f32 v[18:19], v[22:23], v[102:103], v[18:19] op_sel_hi:[1,0,1]
	v_pk_fma_f32 v[48:49], v[158:159], v[106:107], v[48:49]
	v_add_f32_dpp v20, v20, v20 quad_perm:[2,3,0,1] row_mask:0xf bank_mask:0xf bound_ctrl:1
	v_add_f32_e32 v124, v48, v49
	ds_read_b128 v[56:59], v103 offset:41664
	v_add_f32_dpp v20, v20, v20 row_half_mirror row_mask:0xf bank_mask:0xf bound_ctrl:1
	ds_read_b128 v[64:67], v103 offset:41920
	ds_read_b128 v[52:55], v103 offset:42176
	v_add_f32_dpp v20, v20, v20 row_mirror row_mask:0xf bank_mask:0xf bound_ctrl:1
	v_pk_fma_f32 v[12:13], v[12:13], v[20:21], v[16:17] op_sel_hi:[1,0,1]
	v_pk_fma_f32 v[14:15], v[14:15], v[20:21], v[18:19] op_sel_hi:[1,0,1]
	v_pk_mul_f32 v[8:9], v[8:9], v[12:13]
	v_cndmask_b32_e64 v18, v115, v122, s[42:43]
	v_pk_fma_f32 v[8:9], v[10:11], v[14:15], v[8:9]
	s_waitcnt lgkmcnt(7)
	v_pk_mul_f32 v[10:11], v[38:39], v[14:15]
	v_add_f32_e32 v16, v8, v9
	v_pk_mul_f32 v[8:9], v[44:45], v[12:13]
	s_waitcnt lgkmcnt(3)
	v_pk_fma_f32 v[10:11], v[42:43], v[104:105], v[10:11] op_sel_hi:[1,0,1]
	v_pk_fma_f32 v[8:9], v[46:47], v[14:15], v[8:9]
	v_cndmask_b32_e64 v15, v113, v120, s[42:43]
	v_add_f32_e32 v17, v8, v9
	v_pk_mul_f32 v[8:9], v[36:37], v[12:13]
	v_cndmask_b32_e64 v19, v116, v123, s[42:43]
	v_add_f32_dpp v12, v17, v17 quad_perm:[1,0,3,2] row_mask:0xf bank_mask:0xf bound_ctrl:1
	v_pk_fma_f32 v[8:9], v[40:41], v[104:105], v[8:9] op_sel_hi:[1,0,1]
	v_cndmask_b32_e64 v17, v114, v121, s[42:43]
	v_add_f32_dpp v12, v12, v12 quad_perm:[2,3,0,1] row_mask:0xf bank_mask:0xf bound_ctrl:1
	v_cndmask_b32_e64 v20, v117, v124, s[42:43]
	ds_read_b128 v[60:63], v103 offset:42432
	v_add_f32_dpp v12, v12, v12 row_half_mirror row_mask:0xf bank_mask:0xf bound_ctrl:1
	ds_read_b128 v[48:51], v103 offset:42688
	ds_read_b32 v110, v91 offset:42944
	v_add_f32_dpp v12, v12, v12 row_mirror row_mask:0xf bank_mask:0xf bound_ctrl:1
	v_pk_fma_f32 v[8:9], v[32:33], v[12:13], v[8:9] op_sel_hi:[1,0,1]
	v_pk_fma_f32 v[10:11], v[34:35], v[12:13], v[10:11] op_sel_hi:[1,0,1]
	v_pk_mul_f32 v[12:13], v[28:29], v[8:9]
	s_nop 0
	v_pk_fma_f32 v[12:13], v[30:31], v[10:11], v[12:13]
	s_nop 0
	v_add_f32_e32 v14, v12, v13
	s_waitcnt lgkmcnt(0)
	v_pk_mul_f32 v[12:13], v[64:65], v[8:9]
	v_pk_mul_f32 v[8:9], v[56:57], v[8:9]
	v_pk_fma_f32 v[12:13], v[66:67], v[10:11], v[12:13]
	v_pk_fma_f32 v[8:9], v[60:61], v[110:111], v[8:9] op_sel_hi:[1,0,1]
	v_add_f32_e32 v12, v12, v13
	v_pk_mul_f32 v[10:11], v[58:59], v[10:11]
	s_nop 0
	v_add_f32_dpp v12, v12, v12 quad_perm:[1,0,3,2] row_mask:0xf bank_mask:0xf bound_ctrl:1
	v_pk_fma_f32 v[10:11], v[62:63], v[110:111], v[10:11] op_sel_hi:[1,0,1]
	s_nop 0
	v_add_f32_dpp v12, v12, v12 quad_perm:[2,3,0,1] row_mask:0xf bank_mask:0xf bound_ctrl:1
	s_nop 1
	v_add_f32_dpp v12, v12, v12 row_half_mirror row_mask:0xf bank_mask:0xf bound_ctrl:1
	s_nop 1
	v_add_f32_dpp v12, v12, v12 row_mirror row_mask:0xf bank_mask:0xf bound_ctrl:1
	v_pk_fma_f32 v[8:9], v[52:53], v[12:13], v[8:9] op_sel_hi:[1,0,1]
	v_pk_fma_f32 v[10:11], v[54:55], v[12:13], v[10:11] op_sel_hi:[1,0,1]
	v_pk_mul_f32 v[12:13], v[48:49], v[8:9]
	s_nop 0
	v_pk_fma_f32 v[12:13], v[50:51], v[10:11], v[12:13]
	s_nop 0
	v_add_f32_e32 v12, v12, v13
	v_cndmask_b32_e64 v13, v120, v113, s[42:43]
	s_nop 1
	v_add_f32_dpp v13, v15, v13 row_ror:8 row_mask:0xf bank_mask:0xf bound_ctrl:1
	v_cndmask_b32_e64 v15, v121, v114, s[42:43]
	s_nop 1
	v_add_f32_dpp v15, v17, v15 row_ror:8 row_mask:0xf bank_mask:0xf bound_ctrl:1
	v_cndmask_b32_e64 v17, v122, v115, s[42:43]
	s_nop 1
	v_add_f32_dpp v17, v18, v17 row_ror:8 row_mask:0xf bank_mask:0xf bound_ctrl:1
	v_cndmask_b32_e64 v18, v123, v116, s[42:43]
	s_nop 1
	v_add_f32_dpp v18, v19, v18 row_ror:8 row_mask:0xf bank_mask:0xf bound_ctrl:1
	v_cndmask_b32_e64 v19, v124, v117, s[42:43]
	s_nop 1
	v_add_f32_dpp v19, v20, v19 row_ror:8 row_mask:0xf bank_mask:0xf bound_ctrl:1
	v_cndmask_b32_e64 v20, v16, v111, s[42:43]
	v_cndmask_b32_e64 v16, v111, v16, s[42:43]
	s_nop 1
	v_add_f32_dpp v16, v16, v20 row_ror:8 row_mask:0xf bank_mask:0xf bound_ctrl:1
	v_cndmask_b32_e64 v20, v14, v118, s[42:43]
	v_cndmask_b32_e64 v14, v118, v14, s[42:43]
	s_nop 1
	v_add_f32_dpp v14, v14, v20 row_ror:8 row_mask:0xf bank_mask:0xf bound_ctrl:1
	v_cndmask_b32_e64 v20, v12, v119, s[42:43]
	v_cndmask_b32_e64 v12, v119, v12, s[42:43]
	s_nop 1
	v_add_f32_dpp v12, v12, v20 row_ror:8 row_mask:0xf bank_mask:0xf bound_ctrl:1
	v_cndmask_b32_e64 v20, v19, v13, s[44:45]
	v_cndmask_b32_e64 v13, v13, v19, s[44:45]
	v_cndmask_b32_e64 v19, v16, v15, s[44:45]
	v_cndmask_b32_e64 v15, v15, v16, s[44:45]
	v_cndmask_b32_e64 v16, v14, v17, s[44:45]
	v_cndmask_b32_e64 v14, v17, v14, s[44:45]
	v_add_f32_dpp v13, v13, v20 row_half_mirror row_mask:0xf bank_mask:0xf bound_ctrl:1
	v_add_f32_dpp v15, v15, v19 row_half_mirror row_mask:0xf bank_mask:0xf bound_ctrl:1
	v_add_f32_dpp v14, v14, v16 row_half_mirror row_mask:0xf bank_mask:0xf bound_ctrl:1
	v_cndmask_b32_e64 v16, v12, v18, s[44:45]
	v_cndmask_b32_e64 v12, v18, v12, s[44:45]
	s_nop 1
	v_add_f32_dpp v12, v12, v16 row_half_mirror row_mask:0xf bank_mask:0xf bound_ctrl:1
	v_cndmask_b32_e64 v16, v14, v13, s[46:47]
	v_cndmask_b32_e64 v13, v13, v14, s[46:47]
	v_cndmask_b32_e64 v14, v12, v15, s[46:47]
	v_cndmask_b32_e64 v12, v15, v12, s[46:47]
	v_add_f32_dpp v13, v13, v16 quad_perm:[2,3,0,1] row_mask:0xf bank_mask:0xf bound_ctrl:1
	s_nop 0
	v_add_f32_dpp v12, v12, v14 quad_perm:[2,3,0,1] row_mask:0xf bank_mask:0xf bound_ctrl:1
	v_cndmask_b32_e64 v14, v12, v13, s[48:49]
	v_cndmask_b32_e64 v12, v13, v12, s[48:49]
	s_nop 1
	v_add_f32_dpp v12, v12, v14 quad_perm:[1,0,3,2] row_mask:0xf bank_mask:0xf bound_ctrl:1
	ds_write_b32 v97, v12 offset:44032
	s_cbranch_vccnz .LBB0_194
	v_cvt_f32_f16_e32 v16, v74
	v_cvt_f32_f16_sdwa v17, v74 dst_sel:DWORD dst_unused:UNUSED_PAD src0_sel:WORD_1
	v_cvt_f32_f16_e32 v22, v75
	v_cvt_f32_f16_sdwa v23, v75 dst_sel:DWORD dst_unused:UNUSED_PAD src0_sel:WORD_1
	v_lshlrev_b32_e32 v28, 16, v72
	v_and_b32_e32 v29, 0xffff0000, v72
	v_cvt_f32_f16_sdwa v31, v76 dst_sel:DWORD dst_unused:UNUSED_PAD src0_sel:WORD_1
	v_cvt_f32_f16_e32 v30, v76
	v_pk_mul_f32 v[18:19], v[0:1], v[28:29]
	v_cvt_f32_f16_sdwa v35, v77 dst_sel:DWORD dst_unused:UNUSED_PAD src0_sel:WORD_1
	v_cvt_f32_f16_e32 v34, v77
	v_mul_f32_e32 v16, 0x3fb8aa3b, v16
	v_mul_f32_e32 v17, 0x3fb8aa3b, v17
	v_pk_mul_f32 v[20:21], v[78:79], v[18:19] op_sel_hi:[0,1]
	v_mul_f32_e32 v18, 0x3fb8aa3b, v22
	v_mul_f32_e32 v19, 0x3fb8aa3b, v23
	v_lshlrev_b32_e32 v32, 16, v73
	v_and_b32_e32 v33, 0xffff0000, v73
	v_exp_f32_e32 v16, v16
	v_exp_f32_e32 v17, v17
	v_exp_f32_e32 v18, v18
	v_exp_f32_e32 v19, v19
	v_pk_mul_f32 v[22:23], v[2:3], v[32:33]
	v_pk_mul_f32 v[24:25], v[30:31], v[20:21] neg_lo:[0,1] neg_hi:[0,1]
	v_pk_mul_f32 v[22:23], v[78:79], v[22:23] op_sel_hi:[0,1]
	v_pk_mul_f32 v[26:27], v[34:35], v[22:23] neg_lo:[0,1] neg_hi:[0,1]
	v_pk_add_f32 v[30:31], v[30:31], -1.0 op_sel_hi:[1,0]
	v_pk_add_f32 v[34:35], v[34:35], -1.0 op_sel_hi:[1,0]
	v_pk_fma_f32 v[36:37], v[4:5], v[30:31], 1.0 op_sel_hi:[1,1,0]
	v_pk_fma_f32 v[34:35], v[6:7], v[34:35], 1.0 op_sel_hi:[1,1,0]
	v_lshlrev_b32_e32 v12, 16, v70
	v_and_b32_e32 v13, 0xffff0000, v70
	v_lshlrev_b32_e32 v14, 16, v71
	v_and_b32_e32 v15, 0xffff0000, v71
	v_pk_mul_f32 v[30:31], v[34:35], v[32:33]
	v_pk_mul_f32 v[28:29], v[36:37], v[28:29]
	ds_write_b128 v79, v[16:19]
	ds_write_b128 v79, v[20:23] offset:256
	ds_write_b128 v79, v[24:27] offset:512
	ds_write_b128 v79, v[28:31] offset:768
	ds_write_b128 v79, v[12:15] offset:1024
	s_and_saveexec_b64 s[50:51], s[40:41]
	s_cbranch_execz .LBB0_193
	v_lshlrev_b32_e32 v12, 16, v68
	v_and_b32_e32 v13, 0xffff0000, v68
	v_lshlrev_b32_e32 v14, 16, v69
	v_and_b32_e32 v15, 0xffff0000, v69
	ds_write_b128 v79, v[12:15] offset:1280
	s_branch .LBB0_193
	s_nop 0
	s_nop 0
	s_nop 0
	s_nop 0
	s_nop 0
	s_nop 0
	s_nop 0
	s_nop 0
	s_nop 0
	s_nop 0
	s_nop 0
	s_nop 0
